# scan phase: loader/consumer split, LDS-DMA double-buffered chunk images (no VGPR staging), default cache policy
# speedup vs baseline: 1.0045x; 1.0045x over previous
; #define PG8_LAS __attribute__((address_space(3)))
; __device__ __forceinline__ void phase_scan(const Args& a, PG8_LAS unsigned char* lds, int sblk) {
;     const int tid = threadIdx.x, lane = tid & 63, wave = tid >> 6, q = lane >> 4, r = lane & 15;
;     const int bh = sblk >> 1, dvh = sblk & 1, b = bh >> 2, h = bh & 3;
;     bf16_t* of = (bf16_t*)(a.ws + WS_OF2); const float* glast = (const float*)(a.ws + WS_GL);
;     constexpr int L_W = 0, L_QG = 17408, L_KD = 34816, L_UT = 53248, L_AQ = 71680;
;     f32x4 S[8];
; #pragma unroll
;     for (int m = 0; m < 8; ++m) S[m] = (f32x4){0.f, 0.f, 0.f, 0.f};
;     u32x4 pre[9];
;     { const unsigned char* src = a.ws + WS_PREP + (size_t)((b * 32 + 0) * 4 + h) * PREP_ITEM;
; #pragma unroll
;       for (int i = 0; i < 9; ++i) pre[i] = __builtin_nontemporal_load((const u32x4*)(src + (size_t)(tid + 512 * i) * 16)); }
;     for (int n = 0; n < 32; ++n) {
; #pragma unroll
;         for (int i = 0; i < 9; ++i) { const int p = tid + 512 * i; int off;
;             if (i < 2) off = L_W + (p >> 4) * 272 + (p & 15) * 16;
;             else if (i < 4) { const int pp = p - 1024; off = L_QG + (pp >> 4) * 272 + (pp & 15) * 16; }
;             else if (i < 6) { const int pp = p - 2048; off = L_KD + (pp >> 3) * 144 + (pp & 7) * 16; }
;             else if (i < 8) { const int pp = p - 3072; off = L_UT + (pp >> 3) * 144 + (pp & 7) * 16; }
;             else { const int pp = p - 4096; off = L_AQ + (pp >> 3) * 144 + (pp & 7) * 16; }
;             *(PG8_LAS u32x4*)(lds + off) = pre[i]; }
.LBB0_523:
	s_andn2_b64 vcc, exec, s[0:1]
	s_cbranch_vccnz .LBB0_531
	v_readlane_b32 s0, v253, 17
	s_bitcmp0_b32 s0, 4
	s_mov_b32 s5, 0
	s_cbranch_scc1 .LBB0_531
	s_lshr_b32 s4, s82, 3
	s_bfe_u32 s8, s82, 0x20001
	s_and_b32 s30, s82, 1
	s_add_u32 s12, s16, 0x16000000
	s_addc_u32 s13, s17, 0
	s_lshl_b32 s0, s4, 7
	s_or_b32 s20, s0, s8
	s_mul_i32 s0, s20, 0x12000
	s_add_u32 s58, s12, s0
	s_addc_u32 s59, s13, 0
	v_mov_b32_e32 v95, 0
	s_waitcnt vmcnt(0)
	v_readfirstlane_b32 s56, v152
	s_mov_b32 s57, 0
	s_lshr_b32 s56, s56, 6
	s_cmp_lt_u32 s56, 4
	s_cbranch_scc1 .Lsc_consumer
	s_cmp_lt_u32 s56, 6
	s_mov_b32 s69, 0x1c72
	s_cselect_b32 s69, 0xf10, s69
	s_cselect_b32 s70, 17, 9
	s_cselect_b32 s71, 15, 7
	s_movk_i32 s72, 0x80
	s_cselect_b32 s72, 0x100, s72
	s_mov_b32 s75, 0
	s_cmp_eq_u32 s56, 4
	s_cbranch_scc1 .Lsc_ld_w4
	s_cmp_eq_u32 s56, 5
	s_cbranch_scc1 .Lsc_ld_w5
	s_cmp_eq_u32 s56, 6
	s_cbranch_scc1 .Lsc_ld_w6
	s_mov_b32 s73, 0x10000
	s_lshl_b32 s74, s30, 13
	s_add_i32 s74, s74, 0xc000
	s_mov_b32 s75, 0xfffffdc0
	s_mov_b32 s60, 71680
	s_mov_b32 s62, 217344
	s_mul_i32 s61, s30, 0x2400
	s_add_i32 s61, s61, 44032
	s_xor_b32 s63, s61, 106496
	s_branch .Lsc_ld_tab
.Lsc_ld_w4:
	s_mov_b32 s73, 0
	s_mov_b32 s74, 0
	s_mov_b32 s60, 0
	s_mov_b32 s62, 80896
	s_mov_b32 s61, 0
	s_mov_b32 s63, 80896
	s_branch .Lsc_ld_tab
.Lsc_ld_w5:
	s_mov_b32 s73, 0x4000
	s_mov_b32 s74, 0x4000
	s_mov_b32 s60, 17408
	s_mov_b32 s62, 115712
	s_mov_b32 s61, 17408
	s_mov_b32 s63, 115712
	s_branch .Lsc_ld_tab
.Lsc_ld_w6:
	s_mov_b32 s73, 0x8000
	s_mov_b32 s74, 0x8000
	s_mov_b32 s60, 34816
	s_mov_b32 s62, 166144
	s_mov_b32 s61, 34816
	s_mov_b32 s63, 166144
.Lsc_ld_tab:
	v_and_b32_e32 v165, 63, v152
	v_add_u32_e32 v156, 0, v165
	v_mul_u32_u24_e32 v157, s69, v156
	v_lshrrev_b32_e32 v157, 16, v157
	v_mul_u32_u24_e32 v158, s70, v157
	v_sub_u32_e32 v158, v156, v158
	v_min_u32_e32 v158, s71, v158
	v_lshlrev_b32_e32 v158, 4, v158
	v_mad_u32_u24 v170, v157, s72, v158
	v_add_u32_e32 v170, s73, v170
	v_add_u32_e32 v156, 64, v165
	v_mul_u32_u24_e32 v157, s69, v156
	v_lshrrev_b32_e32 v157, 16, v157
	v_mul_u32_u24_e32 v158, s70, v157
	v_sub_u32_e32 v158, v156, v158
	v_min_u32_e32 v158, s71, v158
	v_lshlrev_b32_e32 v158, 4, v158
	v_mad_u32_u24 v171, v157, s72, v158
	v_add_u32_e32 v171, s73, v171
	v_add_u32_e32 v156, 0x80, v165
	v_mul_u32_u24_e32 v157, s69, v156
	v_lshrrev_b32_e32 v157, 16, v157
	v_mul_u32_u24_e32 v158, s70, v157
	v_sub_u32_e32 v158, v156, v158
	v_min_u32_e32 v158, s71, v158
	v_lshlrev_b32_e32 v158, 4, v158
	v_mad_u32_u24 v172, v157, s72, v158
	v_add_u32_e32 v172, s73, v172
	v_add_u32_e32 v156, 0xc0, v165
	v_mul_u32_u24_e32 v157, s69, v156
	v_lshrrev_b32_e32 v157, 16, v157
	v_mul_u32_u24_e32 v158, s70, v157
	v_sub_u32_e32 v158, v156, v158
	v_min_u32_e32 v158, s71, v158
	v_lshlrev_b32_e32 v158, 4, v158
	v_mad_u32_u24 v173, v157, s72, v158
	v_add_u32_e32 v173, s73, v173
	v_add_u32_e32 v156, 0x100, v165
	v_mul_u32_u24_e32 v157, s69, v156
	v_lshrrev_b32_e32 v157, 16, v157
	v_mul_u32_u24_e32 v158, s70, v157
	v_sub_u32_e32 v158, v156, v158
	v_min_u32_e32 v158, s71, v158
	v_lshlrev_b32_e32 v158, 4, v158
	v_mad_u32_u24 v174, v157, s72, v158
	v_add_u32_e32 v174, s73, v174
	v_add_u32_e32 v156, 0x140, v165
	v_mul_u32_u24_e32 v157, s69, v156
	v_lshrrev_b32_e32 v157, 16, v157
	v_mul_u32_u24_e32 v158, s70, v157
	v_sub_u32_e32 v158, v156, v158
	v_min_u32_e32 v158, s71, v158
	v_lshlrev_b32_e32 v158, 4, v158
	v_mad_u32_u24 v175, v157, s72, v158
	v_add_u32_e32 v175, s73, v175
	v_add_u32_e32 v156, 0x180, v165
	v_mul_u32_u24_e32 v157, s69, v156
	v_lshrrev_b32_e32 v157, 16, v157
	v_mul_u32_u24_e32 v158, s70, v157
	v_sub_u32_e32 v158, v156, v158
	v_min_u32_e32 v158, s71, v158
	v_lshlrev_b32_e32 v158, 4, v158
	v_mad_u32_u24 v176, v157, s72, v158
	v_add_u32_e32 v176, s73, v176
	v_add_u32_e32 v156, 0x1c0, v165
	v_mul_u32_u24_e32 v157, s69, v156
	v_lshrrev_b32_e32 v157, 16, v157
	v_mul_u32_u24_e32 v158, s70, v157
	v_sub_u32_e32 v158, v156, v158
	v_min_u32_e32 v158, s71, v158
	v_lshlrev_b32_e32 v158, 4, v158
	v_mad_u32_u24 v177, v157, s72, v158
	v_add_u32_e32 v177, s73, v177
	v_add_u32_e32 v156, 0x200, v165
	v_mul_u32_u24_e32 v157, s69, v156
	v_lshrrev_b32_e32 v157, 16, v157
	v_mul_u32_u24_e32 v158, s70, v157
	v_sub_u32_e32 v158, v156, v158
	v_min_u32_e32 v158, s71, v158
	v_lshlrev_b32_e32 v158, 4, v158
	v_mad_u32_u24 v178, v157, s72, v158
	v_add_u32_e32 v178, s73, v178
	v_add_u32_e32 v156, 0x240, v165
	v_add_u32_e32 v156, s75, v156
	v_mul_u32_u24_e32 v157, s69, v156
	v_lshrrev_b32_e32 v157, 16, v157
	v_mul_u32_u24_e32 v158, s70, v157
	v_sub_u32_e32 v158, v156, v158
	v_min_u32_e32 v158, s71, v158
	v_lshlrev_b32_e32 v158, 4, v158
	v_mad_u32_u24 v179, v157, s72, v158
	v_add_u32_e32 v179, s74, v179
	v_add_u32_e32 v156, 0x280, v165
	v_add_u32_e32 v156, s75, v156
	v_mul_u32_u24_e32 v157, s69, v156
	v_lshrrev_b32_e32 v157, 16, v157
	v_mul_u32_u24_e32 v158, s70, v157
	v_sub_u32_e32 v158, v156, v158
	v_min_u32_e32 v158, s71, v158
	v_lshlrev_b32_e32 v158, 4, v158
	v_mad_u32_u24 v180, v157, s72, v158
	v_add_u32_e32 v180, s74, v180
	v_add_u32_e32 v156, 0x2c0, v165
	v_add_u32_e32 v156, s75, v156
	v_mul_u32_u24_e32 v157, s69, v156
	v_lshrrev_b32_e32 v157, 16, v157
	v_mul_u32_u24_e32 v158, s70, v157
	v_sub_u32_e32 v158, v156, v158
	v_min_u32_e32 v158, s71, v158
	v_lshlrev_b32_e32 v158, 4, v158
	v_mad_u32_u24 v181, v157, s72, v158
	v_add_u32_e32 v181, s74, v181
	v_add_u32_e32 v156, 0x300, v165
	v_add_u32_e32 v156, s75, v156
	v_mul_u32_u24_e32 v157, s69, v156
	v_lshrrev_b32_e32 v157, 16, v157
	v_mul_u32_u24_e32 v158, s70, v157
	v_sub_u32_e32 v158, v156, v158
	v_min_u32_e32 v158, s71, v158
	v_lshlrev_b32_e32 v158, 4, v158
; #define PG8_LAS __attribute__((address_space(3)))
; __device__ __forceinline__ void phase_scan(const Args& a, PG8_LAS unsigned char* lds, int sblk) {
;     ...
;     for (int n = 0; n < 32; ++n) {
; #pragma unroll
;         for (int i = 0; i < 9; ++i) { const int p = tid + 512 * i; int off;
;             if (i < 2) off = L_W + (p >> 4) * 272 + (p & 15) * 16;
;             else if (i < 4) { const int pp = p - 1024; off = L_QG + (pp >> 4) * 272 + (pp & 15) * 16; }
;             else if (i < 6) { const int pp = p - 2048; off = L_KD + (pp >> 3) * 144 + (pp & 7) * 16; }
;             else if (i < 8) { const int pp = p - 3072; off = L_UT + (pp >> 3) * 144 + (pp & 7) * 16; }
;             else { const int pp = p - 4096; off = L_AQ + (pp >> 3) * 144 + (pp & 7) * 16; }
;             *(PG8_LAS u32x4*)(lds + off) = pre[i]; }
;         __syncthreads();
;         if (n + 1 < 32) { const unsigned char* src = a.ws + WS_PREP + (size_t)((b * 32 + n + 1) * 4 + h) * PREP_ITEM;
; #pragma unroll
;             for (int i = 0; i < 9; ++i) pre[i] = __builtin_nontemporal_load((const u32x4*)(src + (size_t)(tid + 512 * i) * 16)); }
;         if (wave < 4) {
;             __builtin_amdgcn_s_setprio(2);
;             const int dv0 = dvh * 64 + wave * 16; const float gl = glast[(b * 32 + n) * 4 + h]; const size_t row0 = (size_t)b * 2048 + n * 64;
	v_mad_u32_u24 v182, v157, s72, v158
	v_add_u32_e32 v182, s74, v182
	v_add_u32_e32 v156, 0x340, v165
	v_add_u32_e32 v156, s75, v156
	v_mul_u32_u24_e32 v157, s69, v156
	v_lshrrev_b32_e32 v157, 16, v157
	v_mul_u32_u24_e32 v158, s70, v157
	v_sub_u32_e32 v158, v156, v158
	v_min_u32_e32 v158, s71, v158
	v_lshlrev_b32_e32 v158, 4, v158
	v_mad_u32_u24 v183, v157, s72, v158
	v_add_u32_e32 v183, s74, v183
	v_add_u32_e32 v156, 0x380, v165
	v_add_u32_e32 v156, s75, v156
	v_mul_u32_u24_e32 v157, s69, v156
	v_lshrrev_b32_e32 v157, 16, v157
	v_mul_u32_u24_e32 v158, s70, v157
	v_sub_u32_e32 v158, v156, v158
	v_min_u32_e32 v158, s71, v158
	v_lshlrev_b32_e32 v158, 4, v158
	v_mad_u32_u24 v184, v157, s72, v158
	v_add_u32_e32 v184, s74, v184
	v_add_u32_e32 v156, 0x3c0, v165
	v_add_u32_e32 v156, s75, v156
	v_mul_u32_u24_e32 v157, s69, v156
	v_lshrrev_b32_e32 v157, 16, v157
	v_mul_u32_u24_e32 v158, s70, v157
	v_sub_u32_e32 v158, v156, v158
	v_min_u32_e32 v158, s71, v158
	v_lshlrev_b32_e32 v158, 4, v158
	v_mad_u32_u24 v185, v157, s72, v158
	v_add_u32_e32 v185, s74, v185
	v_add_u32_e32 v156, 0x400, v165
	v_add_u32_e32 v156, s75, v156
	v_mul_u32_u24_e32 v157, s69, v156
	v_lshrrev_b32_e32 v157, 16, v157
	v_mul_u32_u24_e32 v158, s70, v157
	v_sub_u32_e32 v158, v156, v158
	v_min_u32_e32 v158, s71, v158
	v_lshlrev_b32_e32 v158, 4, v158
	v_mad_u32_u24 v186, v157, s72, v158
	v_add_u32_e32 v186, s74, v186
	v_add_u32_e32 v156, 0x440, v165
	v_add_u32_e32 v156, s75, v156
	v_mul_u32_u24_e32 v157, s69, v156
	v_lshrrev_b32_e32 v157, 16, v157
	v_mul_u32_u24_e32 v158, s70, v157
	v_sub_u32_e32 v158, v156, v158
	v_min_u32_e32 v158, s71, v158
	v_lshlrev_b32_e32 v158, 4, v158
	v_mad_u32_u24 v187, v157, s72, v158
	v_add_u32_e32 v187, s74, v187
.Lsc_ld_loop:
	s_cmp_ge_u32 s57, 32
	s_cbranch_scc1 .Lsc_ld_wait
	s_mov_b32 m0, s60
	s_nop 0
	global_load_lds_dwordx4 v170, s[58:59]
	s_add_i32 m0, s60, 0x400
	s_nop 0
	global_load_lds_dwordx4 v171, s[58:59]
	s_add_i32 m0, s60, 0x800
	s_nop 0
	global_load_lds_dwordx4 v172, s[58:59]
	s_add_i32 m0, s60, 0xc00
	s_nop 0
	global_load_lds_dwordx4 v173, s[58:59]
	s_add_i32 m0, s60, 0x1000
	s_nop 0
	global_load_lds_dwordx4 v174, s[58:59]
	s_add_i32 m0, s60, 0x1400
	s_nop 0
	global_load_lds_dwordx4 v175, s[58:59]
	s_add_i32 m0, s60, 0x1800
	s_nop 0
	global_load_lds_dwordx4 v176, s[58:59]
	s_add_i32 m0, s60, 0x1c00
	s_nop 0
	global_load_lds_dwordx4 v177, s[58:59]
	s_add_i32 m0, s60, 0x2000
	s_nop 0
	global_load_lds_dwordx4 v178, s[58:59]
	s_add_i32 m0, s61, 0x2400
	s_nop 0
	global_load_lds_dwordx4 v179, s[58:59]
	s_add_i32 m0, s61, 0x2800
	s_nop 0
	global_load_lds_dwordx4 v180, s[58:59]
	s_add_i32 m0, s61, 0x2c00
	s_nop 0
	global_load_lds_dwordx4 v181, s[58:59]
	s_add_i32 m0, s61, 0x3000
	s_nop 0
	global_load_lds_dwordx4 v182, s[58:59]
	s_add_i32 m0, s61, 0x3400
	s_nop 0
	global_load_lds_dwordx4 v183, s[58:59]
	s_add_i32 m0, s61, 0x3800
	s_nop 0
	global_load_lds_dwordx4 v184, s[58:59]
	s_add_i32 m0, s61, 0x3c00
	s_nop 0
	global_load_lds_dwordx4 v185, s[58:59]
	s_add_i32 m0, s61, 0x4000
	s_nop 0
	global_load_lds_dwordx4 v186, s[58:59]
	s_cmp_lt_u32 s56, 6
	s_cbranch_scc1 .Lsc_ld_no17
	s_add_i32 m0, s61, 0x4400
	s_nop 0
	global_load_lds_dwordx4 v187, s[58:59]
.Lsc_ld_no17:
	s_add_u32 s58, s58, 0x48000
	s_addc_u32 s59, s59, 0
	s_xor_b32 s60, s60, s62
	s_xor_b32 s61, s61, s63
.Lsc_ld_wait:
	s_waitcnt vmcnt(0)
	s_barrier
	s_add_i32 s57, s57, 1
	s_cmp_le_u32 s57, 32
	s_cbranch_scc1 .Lsc_ld_loop
	s_branch .LBB0_531
.Lsc_consumer:
	s_add_u32 s84, s16, 0x1b00000
	s_addc_u32 s85, s17, 0
	s_lshl_b32 s0, s20, 2
	s_add_u32 s84, s84, s0
	s_addc_u32 s85, s85, 0
	v_and_b32_e32 v155, 31, v152
	v_lshlrev_b32_e32 v155, 4, v155
	global_load_dword v154, v155, s[84:85]
	v_lshrrev_b32_e32 v37, 2, v152
	s_lshl_b32 s9, s82, 6
	v_and_b32_e32 v37, 48, v37
	v_and_b32_e32 v39, 15, v152
	v_and_or_b32 v37, s9, 64, v37
	v_or_b32_e32 v42, v37, v39
	s_movk_i32 s9, 0x90
	v_bfe_u32 v36, v152, 4, 2
	v_mad_u32_u24 v42, v42, s9, 0
	s_add_i32 s9, 0, 0x11800
	s_lshl_b32 s8, s8, 8
	v_lshlrev_b32_e32 v44, 4, v36
	s_add_u32 s8, s16, s8
	v_add_u32_e32 v107, 0, v44
	v_add_u32_e32 v44, s9, v44
	s_addc_u32 s9, s17, 0
	v_lshlrev_b32_e32 v94, 1, v37
	v_lshlrev_b32_e32 v43, 3, v36
	v_lshlrev_b32_e32 v45, 2, v36
	v_lshl_add_u64 v[36:37], s[8:9], 0, v[94:95]
	v_lshlrev_b32_e32 v94, 1, v39
	v_lshl_add_u64 v[36:37], v[36:37], 0, v[94:95]
	s_mov_b64 s[8:9], 0x10000000
	v_lshl_add_u64 v[104:105], v[36:37], 0, s[8:9]
	v_mul_u32_u24_e32 v52, 0x110, v39
	v_mul_u32_u24_e32 v112, 0x90, v39
	v_lshl_or_b32 v94, s4, 11, v45
	v_add_u32_e32 v119, v42, v43
	v_add_u32_e32 v120, v107, v52
	v_add_u32_e32 v121, v44, v112
	v_mov_b64_e32 v[36:37], 0
	v_mov_b64_e32 v[38:39], 0
	v_mov_b64_e32 v[40:41], 0
	v_mov_b64_e32 v[42:43], 0
	v_mov_b64_e32 v[44:45], 0
	v_mov_b64_e32 v[46:47], 0
	v_mov_b64_e32 v[48:49], 0
	v_mov_b64_e32 v[50:51], 0
	v_mov_b64_e32 v[52:53], 0
	v_mov_b64_e32 v[54:55], 0
	v_mov_b64_e32 v[56:57], 0
	v_mov_b64_e32 v[58:59], 0
	v_mov_b64_e32 v[60:61], 0
	v_mov_b64_e32 v[62:63], 0
	v_mov_b64_e32 v[64:65], 0
	v_mov_b64_e32 v[66:67], 0
	s_mov_b32 s64, 0
	s_mov_b32 s65, 0
	s_mov_b32 s66, 0
	s_mov_b32 s67, 0xd000
	s_mul_i32 s68, s30, 0x2400
	s_sub_i32 s68, 168960, s68
	s_waitcnt vmcnt(0)
	s_barrier
; #define PG8_LAS __attribute__((address_space(3)))
; __device__ __forceinline__ float bf_lo(unsigned w) { return __uint_as_float(w << 16); }
; __device__ __forceinline__ float bf_hi(unsigned w) { return __uint_as_float(w & 0xffff0000u); }
; #define MFMA16(a, b, c) __builtin_amdgcn_mfma_f32_16x16x32_bf16((a), (b), (c), 0, 0, 0)
; __device__ __forceinline__ bf16x8 packf8(const f32x4 lo, const f32x4 hi) { u32x4 p; p.x = pk2(lo[0], lo[1]); p.y = pk2(lo[2], lo[3]); p.z = pk2(hi[0], hi[1]); p.w = pk2(hi[2], hi[3]); return __builtin_bit_cast(bf16x8, p); }
; __device__ __forceinline__ void phase_scan(const Args& a, PG8_LAS unsigned char* lds, int sblk) {
;     ...
;         if (wave < 4) {
;             __builtin_amdgcn_s_setprio(2);
;             const int dv0 = dvh * 64 + wave * 16; const float gl = glast[(b * 32 + n) * 4 + h]; const size_t row0 = (size_t)b * 2048 + n * 64;
;             bf16x8 Sb[4];
; #pragma unroll
;             for (int s = 0; s < 4; ++s) Sb[s] = packf8(S[2 * s], S[2 * s + 1]);
;             f32x4 vn[4];
; #pragma unroll
;             for (int mt = 0; mt < 4; ++mt) {
;                 const u32x2 uu = *(const PG8_LAS u32x2*)(lds + L_UT + (dv0 + r) * 144 + (16 * mt + 4 * q) * 2);
;                 f32x4 acc = {0.f, 0.f, 0.f, 0.f};
; #pragma unroll
;                 for (int s = 0; s < 4; ++s) { const bf16x8 af = *(const PG8_LAS bf16x8*)(lds + L_W + (16 * mt + r) * 272 + (32 * s + 8 * q) * 2); acc = MFMA16(af, Sb[s], acc); }
;                 vn[mt] = (f32x4){bf_lo(uu.x), bf_hi(uu.x), bf_lo(uu.y), bf_hi(uu.y)} - acc;
;             }
;             bf16x8 Vb[2];
; #pragma unroll
;             for (int s = 0; s < 2; ++s) Vb[s] = packf8(vn[2 * s], vn[2 * s + 1]);
.Lsc_cs_loop:
	v_readlane_b32 s54, v154, s57
	v_add_u32_e32 v160, s64, v120
	v_add_u32_e32 v161, s66, v121
	s_setprio 2
	v_mov_b32_e32 v106, s54
	v_cvt_pk_bf16_f32 v76, v48, v49
	v_cvt_pk_bf16_f32 v77, v50, v51
	v_cvt_pk_bf16_f32 v78, v44, v45
	v_cvt_pk_bf16_f32 v79, v46, v47
	v_cvt_pk_bf16_f32 v80, v40, v41
	v_cvt_pk_bf16_f32 v81, v42, v43
	v_cvt_pk_bf16_f32 v82, v36, v37
	v_cvt_pk_bf16_f32 v83, v38, v39
	v_cvt_pk_bf16_f32 v84, v56, v57
	v_cvt_pk_bf16_f32 v85, v58, v59
	v_cvt_pk_bf16_f32 v86, v60, v61
	v_cvt_pk_bf16_f32 v87, v62, v63
	v_cvt_pk_bf16_f32 v88, v64, v65
	v_cvt_pk_bf16_f32 v89, v66, v67
	v_cvt_pk_bf16_f32 v90, v52, v53
	v_cvt_pk_bf16_f32 v91, v54, v55
	ds_read_b128 v[68:71], v160
	ds_read_b128 v[72:75], v160 offset:64
	s_waitcnt lgkmcnt(1)
	v_mfma_f32_16x16x32_bf16 v[68:71], v[68:71], v[76:79], 0
	ds_read_b128 v[122:125], v160 offset:128
	ds_read_b128 v[130:133], v160 offset:4480
	ds_read_b128 v[134:137], v160 offset:4544
	s_waitcnt lgkmcnt(3)
	v_mfma_f32_16x16x32_bf16 v[68:71], v[72:75], v[80:83], v[68:71]
	ds_read_b128 v[72:75], v160 offset:192
	v_add_u32_e32 v108, s67, v119
	ds_read2_b64 v[126:129], v108 offset1:4
	s_waitcnt lgkmcnt(4)
	v_mfma_f32_16x16x32_bf16 v[68:71], v[122:125], v[84:87], v[68:71]
	ds_read_b128 v[122:125], v160 offset:4352
	s_waitcnt lgkmcnt(1)
	v_lshlrev_b32_e32 v138, 16, v127
	v_and_b32_e32 v127, 0xffff0000, v127
	v_mfma_f32_16x16x32_bf16 v[68:71], v[72:75], v[88:91], v[68:71]
	ds_read_b128 v[72:75], v160 offset:4416
	v_lshlrev_b32_e32 v109, 16, v126
	v_and_b32_e32 v126, 0xffff0000, v126
	s_waitcnt lgkmcnt(1)
	v_mfma_f32_16x16x32_bf16 v[122:125], v[122:125], v[76:79], 0
	v_pk_mul_f32 v[50:51], v[50:51], v[106:107] op_sel_hi:[1,0]
	s_waitcnt lgkmcnt(0)
	v_mfma_f32_16x16x32_bf16 v[72:75], v[72:75], v[80:83], v[122:125]
	v_sub_f32_e32 v142, v138, v70
	v_sub_f32_e32 v143, v127, v71
	ds_read_b128 v[138:141], v160 offset:8896
	s_nop 0
	ds_read_b128 v[122:125], v160 offset:8704
	v_mfma_f32_16x16x32_bf16 v[72:75], v[130:133], v[84:87], v[72:75]
	ds_read_b128 v[130:133], v160 offset:8768
	v_sub_f32_e32 v109, v109, v68
	v_sub_f32_e32 v144, v126, v69
	v_mfma_f32_16x16x32_bf16 v[70:73], v[134:137], v[88:91], v[72:75]
	ds_read_b128 v[134:137], v160 offset:8832
	v_lshlrev_b32_e32 v68, 16, v128
	v_and_b32_e32 v69, 0xffff0000, v128
	s_waitcnt lgkmcnt(2)
	v_mfma_f32_16x16x32_bf16 v[122:125], v[122:125], v[76:79], 0
	v_lshlrev_b32_e32 v74, 16, v129
	v_and_b32_e32 v75, 0xffff0000, v129
	ds_read_b128 v[126:129], v160 offset:13056
	s_waitcnt lgkmcnt(2)
	v_mfma_f32_16x16x32_bf16 v[122:125], v[130:133], v[80:83], v[122:125]
	v_sub_f32_e32 v145, v74, v72
	v_sub_f32_e32 v146, v75, v73
	ds_read2_b64 v[72:75], v108 offset0:8 offset1:12
	ds_read_b128 v[130:133], v160 offset:13120
	s_waitcnt lgkmcnt(3)
	v_mfma_f32_16x16x32_bf16 v[122:125], v[134:137], v[84:87], v[122:125]
	v_sub_f32_e32 v108, v68, v70
	ds_read_b128 v[134:137], v160 offset:13248
	v_pk_mul_f32 v[48:49], v[48:49], v[106:107] op_sel_hi:[1,0]
	v_mfma_f32_16x16x32_bf16 v[122:125], v[138:141], v[88:91], v[122:125]
	v_sub_f32_e32 v138, v69, v71
	ds_read_b128 v[68:71], v160 offset:13184
	s_waitcnt lgkmcnt(3)
	v_lshlrev_b32_e32 v139, 16, v72
	v_mfma_f32_16x16x32_bf16 v[126:129], v[126:129], v[76:79], 0
	v_and_b32_e32 v72, 0xffff0000, v72
	s_nop 1
	v_sub_f32_e32 v123, v72, v123
	v_lshlrev_b32_e32 v72, 16, v74
	s_waitcnt lgkmcnt(2)
	v_mfma_f32_16x16x32_bf16 v[126:129], v[130:133], v[80:83], v[126:129]
	v_lshlrev_b32_e32 v130, 16, v73
	v_and_b32_e32 v73, 0xffff0000, v73
	v_sub_f32_e32 v125, v73, v125
	s_waitcnt lgkmcnt(0)
	v_mfma_f32_16x16x32_bf16 v[68:71], v[68:71], v[84:87], v[126:129]
	v_and_b32_e32 v73, 0xffff0000, v74
	v_lshlrev_b32_e32 v74, 16, v75
	v_and_b32_e32 v75, 0xffff0000, v75
	v_mfma_f32_16x16x32_bf16 v[68:71], v[134:137], v[88:91], v[68:71]
	v_sub_f32_e32 v124, v130, v124
	v_sub_f32_e32 v122, v139, v122
	v_pk_mul_f32 v[46:47], v[46:47], v[106:107] op_sel_hi:[1,0]
	v_pk_mul_f32 v[44:45], v[44:45], v[106:107] op_sel_hi:[1,0]
	v_pk_mul_f32 v[42:43], v[42:43], v[106:107] op_sel_hi:[1,0]
	s_nop 2
	v_sub_f32_e32 v126, v74, v70
	v_sub_f32_e32 v71, v75, v71
	v_sub_f32_e32 v70, v72, v68
	v_sub_f32_e32 v127, v73, v69
	v_cvt_pk_bf16_f32 v72, v109, v144
	v_cvt_pk_bf16_f32 v73, v142, v143
	v_cvt_pk_bf16_f32 v74, v108, v138
	v_cvt_pk_bf16_f32 v75, v145, v146
	v_cvt_pk_bf16_f32 v68, v122, v123
	v_cvt_pk_bf16_f32 v69, v124, v125
	v_cvt_pk_bf16_f32 v70, v70, v127
	v_cvt_pk_bf16_f32 v71, v126, v71
	ds_read_b128 v[122:125], v160 offset:17408
	ds_read_b128 v[126:129], v160 offset:17472
	s_waitcnt lgkmcnt(1)
	v_mfma_f32_16x16x32_bf16 v[122:125], v[122:125], v[76:79], 0
	ds_read_b128 v[130:133], v160 offset:17536
	v_lshlrev_b64 v[108:109], 10, v[94:95]
	v_lshl_add_u64 v[142:143], v[104:105], 0, v[108:109]
	s_waitcnt lgkmcnt(1)
	v_mfma_f32_16x16x32_bf16 v[122:125], v[126:129], v[80:83], v[122:125]
	ds_read_b128 v[126:129], v160 offset:17600
	v_pk_mul_f32 v[40:41], v[40:41], v[106:107] op_sel_hi:[1,0]
	v_pk_mul_f32 v[38:39], v[38:39], v[106:107] op_sel_hi:[1,0]
	s_waitcnt lgkmcnt(1)
	v_mfma_f32_16x16x32_bf16 v[122:125], v[130:133], v[84:87], v[122:125]
	ds_read_b128 v[130:133], v161
	v_pk_mul_f32 v[36:37], v[36:37], v[106:107] op_sel_hi:[1,0]
	v_pk_mul_f32 v[58:59], v[58:59], v[106:107] op_sel_hi:[1,0]
	s_waitcnt lgkmcnt(1)
	v_mfma_f32_16x16x32_bf16 v[122:125], v[126:129], v[88:91], v[122:125]
	ds_read_b128 v[126:129], v161 offset:64
	v_pk_mul_f32 v[56:57], v[56:57], v[106:107] op_sel_hi:[1,0]
	v_pk_mul_f32 v[62:63], v[62:63], v[106:107] op_sel_hi:[1,0]
	s_waitcnt lgkmcnt(1)
; #define PG8_LAS __attribute__((address_space(3)))
; __device__ __forceinline__ unsigned pk2c(float a, float b) { const f32x2_ v = {a, b}; const bf16x2_ r = __builtin_convertvector(v, bf16x2_); return __builtin_bit_cast(unsigned, r); }
; #define MFMA16(a, b, c) __builtin_amdgcn_mfma_f32_16x16x32_bf16((a), (b), (c), 0, 0, 0)
; __device__ __forceinline__ void phase_scan(const Args& a, PG8_LAS unsigned char* lds, int sblk) {
;     ...
; #pragma unroll
;             for (int mt = 0; mt < 4; ++mt) {
;                 f32x4 o = {0.f, 0.f, 0.f, 0.f};
; #pragma unroll
;                 for (int s = 0; s < 4; ++s) { const bf16x8 af = *(const PG8_LAS bf16x8*)(lds + L_QG + (16 * mt + r) * 272 + (32 * s + 8 * q) * 2); o = MFMA16(af, Sb[s], o); }
; #pragma unroll
;                 for (int s = 0; s < 2; ++s) { const bf16x8 af = *(const PG8_LAS bf16x8*)(lds + L_AQ + (16 * mt + r) * 144 + (32 * s + 8 * q) * 2); o = MFMA16(af, Vb[s], o); }
; #pragma unroll
;                 for (int e = 0; e < 4; ++e) of[(row0 + 16 * mt + 4 * q + e) * 512 + h * 128 + dv0 + r] = (bf16_t)(pk2c(o[e], o[e]) & 0xffffu);
;             }
	v_mfma_f32_16x16x32_bf16 v[122:125], v[130:133], v[72:75], v[122:125]
	ds_read_b128 v[130:133], v160 offset:21760
	v_pk_mul_f32 v[60:61], v[60:61], v[106:107] op_sel_hi:[1,0]
	v_pk_mul_f32 v[66:67], v[66:67], v[106:107] op_sel_hi:[1,0]
	s_waitcnt lgkmcnt(1)
	v_mfma_f32_16x16x32_bf16 v[122:125], v[126:129], v[68:71], v[122:125]
	ds_read_b128 v[126:129], v160 offset:21824
	ds_read_b128 v[134:137], v160 offset:21888
	ds_read_b128 v[138:141], v160 offset:21952
	v_pk_mul_f32 v[64:65], v[64:65], v[106:107] op_sel_hi:[1,0]
	s_waitcnt lgkmcnt(3)
	v_mfma_f32_16x16x32_bf16 v[130:133], v[130:133], v[76:79], 0
	s_nop 1
	v_cvt_pk_bf16_f32 v122, v122, s0
	global_store_short v[142:143], v122, off
	v_cvt_pk_bf16_f32 v122, v123, s0
	s_waitcnt lgkmcnt(2)
	v_mfma_f32_16x16x32_bf16 v[126:129], v[126:129], v[80:83], v[130:133]
	global_store_short v[142:143], v122, off offset:1024
	v_cvt_pk_bf16_f32 v122, v124, s0
	global_store_short v[142:143], v122, off offset:2048
	ds_read_b128 v[130:133], v161 offset:2304
	s_waitcnt lgkmcnt(2)
	v_mfma_f32_16x16x32_bf16 v[126:129], v[134:137], v[84:87], v[126:129]
	ds_read_b128 v[134:137], v161 offset:2368
	v_cvt_pk_bf16_f32 v122, v125, s0
	global_store_short v[142:143], v122, off offset:3072
	s_waitcnt lgkmcnt(2)
	v_mfma_f32_16x16x32_bf16 v[126:129], v[138:141], v[88:91], v[126:129]
	v_mul_f32_e64 v54, v54, v106
	v_mul_f32_e64 v55, v55, v106
	v_pk_mul_f32 v[52:53], v[52:53], v[106:107] op_sel_hi:[1,0]
	s_waitcnt lgkmcnt(1)
	v_mfma_f32_16x16x32_bf16 v[126:129], v[130:133], v[72:75], v[126:129]
	v_or_b32_e32 v130, 0x4000, v108
	v_mov_b32_e32 v131, v109
	v_lshl_add_u64 v[130:131], v[104:105], 0, v[130:131]
	s_waitcnt lgkmcnt(0)
	v_mfma_f32_16x16x32_bf16 v[122:125], v[134:137], v[68:71], v[126:129]
	ds_read_b128 v[134:137], v160 offset:26240
	s_nop 1
	ds_read_b128 v[126:129], v160 offset:26112
	s_nop 3
	v_cvt_pk_bf16_f32 v122, v122, s0
	global_store_short v[130:131], v122, off
	ds_read_b128 v[130:133], v160 offset:26176
	s_waitcnt lgkmcnt(1)
	v_mfma_f32_16x16x32_bf16 v[126:129], v[126:129], v[76:79], 0
	v_cvt_pk_bf16_f32 v138, v123, s0
	v_or_b32_e32 v122, 0x4400, v108
	v_mov_b32_e32 v123, v109
	v_lshl_add_u64 v[122:123], v[104:105], 0, v[122:123]
	global_store_short v[122:123], v138, off
	ds_read_b128 v[138:141], v160 offset:26304
	s_waitcnt lgkmcnt(1)
	v_mfma_f32_16x16x32_bf16 v[126:129], v[130:133], v[80:83], v[126:129]
	ds_read_b128 v[130:133], v161 offset:4608
	v_or_b32_e32 v122, 0x4800, v108
	v_mov_b32_e32 v123, v109
	v_mfma_f32_16x16x32_bf16 v[126:129], v[134:137], v[84:87], v[126:129]
	ds_read_b128 v[134:137], v161 offset:4672
	v_cvt_pk_bf16_f32 v124, v124, s0
	v_lshl_add_u64 v[122:123], v[104:105], 0, v[122:123]
	s_waitcnt lgkmcnt(2)
	v_mfma_f32_16x16x32_bf16 v[126:129], v[138:141], v[88:91], v[126:129]
	global_store_short v[122:123], v124, off
	v_cvt_pk_bf16_f32 v140, v125, s0
	v_or_b32_e32 v138, 0x4c00, v108
	s_waitcnt lgkmcnt(1)
	v_mfma_f32_16x16x32_bf16 v[122:125], v[130:133], v[72:75], v[126:129]
	v_mov_b32_e32 v139, v109
	s_nop 1
	v_lshl_add_u64 v[126:127], v[104:105], 0, v[138:139]
	global_store_short v[126:127], v140, off
	s_waitcnt lgkmcnt(0)
	v_mfma_f32_16x16x32_bf16 v[122:125], v[134:137], v[68:71], v[122:125]
	v_or_b32_e32 v126, 0x8000, v108
	v_mov_b32_e32 v127, v109
	v_lshl_add_u64 v[130:131], v[104:105], 0, v[126:127]
	ds_read_b128 v[126:129], v160 offset:30464
	s_nop 3
	v_cvt_pk_bf16_f32 v122, v122, s0
	global_store_short v[130:131], v122, off
	ds_read_b128 v[130:133], v160 offset:30528
	v_cvt_pk_bf16_f32 v134, v123, s0
	v_or_b32_e32 v122, 0x8400, v108
	v_mov_b32_e32 v123, v109
	v_lshl_add_u64 v[122:123], v[104:105], 0, v[122:123]
	global_store_short v[122:123], v134, off
	ds_read_b128 v[134:137], v160 offset:30592
	s_waitcnt lgkmcnt(2)
	v_mfma_f32_16x16x32_bf16 v[76:79], v[126:129], v[76:79], 0
	ds_read_b128 v[126:129], v160 offset:30656
	v_or_b32_e32 v122, 0x8800, v108
	v_mov_b32_e32 v123, v109
	s_waitcnt lgkmcnt(2)
; #define PG8_LAS __attribute__((address_space(3)))
; #define MFMA16(a, b, c) __builtin_amdgcn_mfma_f32_16x16x32_bf16((a), (b), (c), 0, 0, 0)
; __device__ __forceinline__ void phase_scan(const Args& a, PG8_LAS unsigned char* lds, int sblk) {
;     ...
; #pragma unroll
;             for (int mt = 0; mt < 8; ++mt) {
;                 f32x4 acc = S[mt] * gl;
; #pragma unroll
;                 for (int s = 0; s < 2; ++s) { const bf16x8 af = *(const PG8_LAS bf16x8*)(lds + L_KD + (16 * mt + r) * 144 + (32 * s + 8 * q) * 2); acc = MFMA16(af, Vb[s], acc); }
;                 S[mt] = acc;
;             }
;             __builtin_amdgcn_s_setprio(0);
;         }
;         __syncthreads();
;     }
	v_mfma_f32_16x16x32_bf16 v[76:79], v[130:133], v[80:83], v[76:79]
	ds_read_b128 v[80:83], v161 offset:6912
	v_cvt_pk_bf16_f32 v124, v124, s0
	v_lshl_add_u64 v[122:123], v[104:105], 0, v[122:123]
	s_waitcnt lgkmcnt(2)
	v_mfma_f32_16x16x32_bf16 v[76:79], v[134:137], v[84:87], v[76:79]
	ds_read_b128 v[84:87], v161 offset:6976
	global_store_short v[122:123], v124, off
	v_add3_u32 v124, v107, v112, s65
	s_waitcnt lgkmcnt(2)
	v_mfma_f32_16x16x32_bf16 v[76:79], v[126:129], v[88:91], v[76:79]
	v_or_b32_e32 v88, 0x8c00, v108
	v_mov_b32_e32 v89, v109
	v_cvt_pk_bf16_f32 v122, v125, s0
	s_waitcnt lgkmcnt(1)
	v_mfma_f32_16x16x32_bf16 v[76:79], v[80:83], v[72:75], v[76:79]
	ds_read_b128 v[80:83], v124 offset:34816
	v_lshl_add_u64 v[88:89], v[104:105], 0, v[88:89]
	global_store_short v[88:89], v122, off
	s_waitcnt lgkmcnt(1)
	v_mfma_f32_16x16x32_bf16 v[76:79], v[84:87], v[68:71], v[76:79]
	ds_read_b128 v[84:87], v124 offset:34880
	ds_read_b128 v[88:91], v124 offset:37120
	v_or_b32_e32 v122, 0xc000, v108
	s_waitcnt lgkmcnt(2)
	v_mfma_f32_16x16x32_bf16 v[48:51], v[80:83], v[72:75], v[48:51]
	ds_read_b128 v[80:83], v124 offset:37184
	v_mov_b32_e32 v123, v109
	s_nop 0
	v_cvt_pk_bf16_f32 v76, v76, s0
	s_waitcnt lgkmcnt(2)
	v_mfma_f32_16x16x32_bf16 v[48:51], v[84:87], v[68:71], v[48:51]
	ds_read_b128 v[84:87], v124 offset:39424
	v_cvt_pk_bf16_f32 v78, v78, s0
	s_waitcnt lgkmcnt(2)
	v_mfma_f32_16x16x32_bf16 v[44:47], v[88:91], v[72:75], v[44:47]
	v_lshl_add_u64 v[88:89], v[104:105], 0, v[122:123]
	global_store_short v[88:89], v76, off
	ds_read_b128 v[88:91], v124 offset:39488
	s_waitcnt lgkmcnt(2)
	v_mfma_f32_16x16x32_bf16 v[44:47], v[80:83], v[68:71], v[44:47]
	ds_read_b128 v[80:83], v124 offset:41728
	v_cvt_pk_bf16_f32 v122, v77, s0
	v_or_b32_e32 v76, 0xc400, v108
	s_waitcnt lgkmcnt(2)
	v_mfma_f32_16x16x32_bf16 v[40:43], v[84:87], v[72:75], v[40:43]
	ds_read_b128 v[84:87], v124 offset:41792
	v_mov_b32_e32 v77, v109
	v_lshl_add_u64 v[76:77], v[104:105], 0, v[76:77]
	s_waitcnt lgkmcnt(2)
	v_mfma_f32_16x16x32_bf16 v[40:43], v[88:91], v[68:71], v[40:43]
	ds_read_b128 v[88:91], v124 offset:44032
	global_store_short v[76:77], v122, off
	v_or_b32_e32 v76, 0xc800, v108
	s_waitcnt lgkmcnt(2)
	v_mfma_f32_16x16x32_bf16 v[36:39], v[80:83], v[72:75], v[36:39]
	ds_read_b128 v[80:83], v124 offset:44096
	v_mov_b32_e32 v77, v109
	v_lshl_add_u64 v[76:77], v[104:105], 0, v[76:77]
	s_waitcnt lgkmcnt(2)
	v_mfma_f32_16x16x32_bf16 v[36:39], v[84:87], v[68:71], v[36:39]
	ds_read_b128 v[84:87], v124 offset:46336
	v_or_b32_e32 v108, 0xcc00, v108
	global_store_short v[76:77], v78, off
	s_waitcnt lgkmcnt(2)
	v_mfma_f32_16x16x32_bf16 v[56:59], v[88:91], v[72:75], v[56:59]
	ds_read_b128 v[88:91], v124 offset:46400
	v_cvt_pk_bf16_f32 v76, v79, s0
	s_waitcnt lgkmcnt(2)
	v_mfma_f32_16x16x32_bf16 v[56:59], v[80:83], v[68:71], v[56:59]
	ds_read_b128 v[80:83], v124 offset:48640
	s_waitcnt lgkmcnt(2)
	v_mfma_f32_16x16x32_bf16 v[60:63], v[84:87], v[72:75], v[60:63]
	ds_read_b128 v[84:87], v124 offset:48704
	s_waitcnt lgkmcnt(2)
	v_mfma_f32_16x16x32_bf16 v[60:63], v[88:91], v[68:71], v[60:63]
	ds_read_b128 v[88:91], v124 offset:50944
	s_waitcnt lgkmcnt(2)
	v_mfma_f32_16x16x32_bf16 v[64:67], v[80:83], v[72:75], v[64:67]
	ds_read_b128 v[80:83], v124 offset:51008
	s_waitcnt lgkmcnt(1)
	v_mfma_f32_16x16x32_bf16 v[52:55], v[88:91], v[72:75], v[52:55]
	v_lshl_add_u64 v[72:73], v[104:105], 0, v[108:109]
	global_store_short v[72:73], v76, off
	v_mfma_f32_16x16x32_bf16 v[64:67], v[84:87], v[68:71], v[64:67]
	s_waitcnt lgkmcnt(0)
	v_mfma_f32_16x16x32_bf16 v[52:55], v[80:83], v[68:71], v[52:55]
	s_setprio 0
	s_sub_i32 s64, 80896, s64
	s_sub_i32 s65, 96512, s65
	s_sub_i32 s66, 78080, s66
	s_sub_i32 s67, s68, s67
	v_add_u32_e32 v94, 64, v94
	s_waitcnt lgkmcnt(0)
	s_barrier
	s_add_i32 s57, s57, 1
	s_cmp_lt_u32 s57, 32
	s_cbranch_scc1 .Lsc_cs_loop

	.amdhsa_kernel _Z4mega4Args
		.amdhsa_group_segment_fixed_size 19456
		.amdhsa_private_segment_fixed_size 0
		.amdhsa_kernarg_size 416
		.amdhsa_user_sgpr_count 2
		.amdhsa_user_sgpr_dispatch_ptr 0
		.amdhsa_user_sgpr_queue_ptr 0
		.amdhsa_user_sgpr_kernarg_segment_ptr 1
		.amdhsa_user_sgpr_dispatch_id 0
		.amdhsa_user_sgpr_kernarg_preload_length 0
		.amdhsa_user_sgpr_kernarg_preload_offset 0
		.amdhsa_user_sgpr_private_segment_size 0
		.amdhsa_uses_dynamic_stack 0
		.amdhsa_enable_private_segment 0
		.amdhsa_system_sgpr_workgroup_id_x 1
		.amdhsa_system_sgpr_workgroup_id_y 0
		.amdhsa_system_sgpr_workgroup_id_z 0
		.amdhsa_system_sgpr_workgroup_info 0
		.amdhsa_system_vgpr_workitem_id 2
		.amdhsa_next_free_vgpr 254
		.amdhsa_next_free_sgpr 98
		.amdhsa_accum_offset 256
		.amdhsa_reserve_vcc 1
		.amdhsa_float_round_mode_32 0
		.amdhsa_float_round_mode_16_64 0
		.amdhsa_float_denorm_mode_32 3
		.amdhsa_float_denorm_mode_16_64 3
		.amdhsa_dx10_clamp 1
		.amdhsa_ieee_mode 1
		.amdhsa_fp16_overflow 0
		.amdhsa_tg_split 0
		.amdhsa_exception_fp_ieee_invalid_op 0
		.amdhsa_exception_fp_denorm_src 0
		.amdhsa_exception_fp_ieee_div_zero 0
		.amdhsa_exception_fp_ieee_overflow 0
		.amdhsa_exception_fp_ieee_underflow 0
		.amdhsa_exception_fp_ieee_inexact 0
		.amdhsa_exception_int_div_zero 0
	.end_amdhsa_kernel

; __global__ void __launch_bounds__(NT) mega(Args a) {
;     extern __shared__ __attribute__((aligned(16))) unsigned char lds_raw[];
amdhsa.kernels:
  - .agpr_count:     0
    .args:
      - .offset:         0
        .size:           160
        .value_kind:     by_value
      - .offset:         160
        .size:           4
        .value_kind:     hidden_block_count_x
      - .offset:         164
        .size:           4
        .value_kind:     hidden_block_count_y
      - .offset:         168
        .size:           4
        .value_kind:     hidden_block_count_z
      - .offset:         172
        .size:           2
        .value_kind:     hidden_group_size_x
      - .offset:         174
        .size:           2
        .value_kind:     hidden_group_size_y
      - .offset:         176
        .size:           2
        .value_kind:     hidden_group_size_z
      - .offset:         178
        .size:           2
        .value_kind:     hidden_remainder_x
      - .offset:         180
        .size:           2
        .value_kind:     hidden_remainder_y
      - .offset:         182
        .size:           2
        .value_kind:     hidden_remainder_z
      - .offset:         200
        .size:           8
        .value_kind:     hidden_global_offset_x
      - .offset:         208
        .size:           8
        .value_kind:     hidden_global_offset_y
      - .offset:         216
        .size:           8
        .value_kind:     hidden_global_offset_z
      - .offset:         224
        .size:           2
        .value_kind:     hidden_grid_dims
      - .offset:         248
        .size:           8
        .value_kind:     hidden_multigrid_sync_arg
      - .offset:         280
        .size:           4
        .value_kind:     hidden_dynamic_lds_size
    .group_segment_fixed_size: 19456
    .kernarg_segment_align: 8
    .kernarg_segment_size: 416
    .language:       OpenCL C
    .language_version:
      - 2
      - 0
    .max_flat_workgroup_size: 512
    .name:           _Z4mega4Args
    .private_segment_fixed_size: 0
    .sgpr_count:     104
    .sgpr_spill_count: 98
    .symbol:         _Z4mega4Args.kd
    .uniform_work_group_size: 1
    .uses_dynamic_stack: false
    .vgpr_count:     254
    .vgpr_spill_count: 0
    .wavefront_size: 64
